# v12 with the code after the attention region shifted by +32 bytes (placement)
# speedup vs baseline: 1.0061x; 1.0061x over previous
; __device__ __forceinline__ void xcd_barrier(const XcdBarrier& b) {
;     asm volatile("s_waitcnt vmcnt(0)" ::: "memory");
; __global__ void __launch_bounds__(512, 2) fwd_kernel(Params p) {
;     ...
;             phase_attn(p, l, lds);
;             xcd_barrier(xb);
.Lat_end:
	v_readlane_b32 s52, v243, 41
	v_readlane_b32 s53, v243, 42
	v_readlane_b32 s80, v252, 4
	v_readlane_b32 s81, v252, 5
	v_readlane_b32 s82, v252, 6
	v_readlane_b32 s83, v252, 7
	v_readlane_b32 s84, v252, 8
	v_readlane_b32 s85, v252, 9
	v_readlane_b32 s86, v252, 10
	v_readlane_b32 s87, v252, 11
	v_readlane_b32 s88, v252, 12
	v_readlane_b32 s89, v252, 13
	v_readlane_b32 s90, v252, 14
	v_readlane_b32 s91, v252, 15
	v_readlane_b32 s92, v252, 16
	v_readlane_b32 s93, v252, 17
	v_readlane_b32 s94, v252, 18
	v_readlane_b32 s95, v252, 19
	s_waitcnt vmcnt(0)
	.p2align 8
	s_nop 0
	s_nop 0
	s_nop 0
	s_nop 0
	s_nop 0
	s_nop 0
	s_nop 0
	s_nop 0
	s_nop 0
	s_nop 0
	s_nop 0
	s_nop 0
	s_nop 0
	s_nop 0
	s_nop 0
	s_nop 0
	s_nop 0
	s_nop 0
	s_nop 0
	s_nop 0
	s_nop 0
	s_nop 0
	s_nop 0
	s_nop 0
	s_nop 0
	s_nop 0
	s_nop 0
